# LN1/LN2 wave reductions: DPP-operand adds and permlane16/32 swaps instead of six ds_bpermute round trips (same butterfly)
# baseline (speedup 1.0000x reference)
; DI void row_normalize(float (&v)[32]) {
;     float s = 0.f;
; #pragma unroll
;     for (int i = 0; i < 32; ++i) s += v[i];
;     const float mean = wave_sum(s) * (1.0f / D);
; DI void phase_ln1(int l, int nrows, int wv) {
;     ...
;     for (int r = gw; r < nrows; r += NGW) {
;         const float* md = F.mod + ((size_t)l * 9 + modrow(r)) * MODW;
;         float v[32], t[32];
;         load_row_f32(xrow(xin, cin, F.X, l, r), F.lane, v);
;         load_row_bf16(F.H + (size_t)r * D, F.lane, t);
;         { float g1[32]; load_row_f32(md + 2 * D, F.lane, g1);
; #pragma unroll
;           for (int i = 0; i < 32; ++i) v[i] = ALPHA * v[i] + g1[i] * t[i]; }
.LBB0_775:
	s_ashr_i32 s14, s4, 31
	s_lshr_b32 s14, s14, 21
	s_add_i32 s14, s4, s14
	s_ashr_i32 s14, s14, 11
	s_and_b64 s[10:11], s[10:11], exec
	s_cselect_b32 s10, s14, 8
	s_ashr_i32 s11, s10, 31
	s_mul_i32 s14, s92, 9
	s_add_u32 s10, s14, s10
	s_addc_u32 s11, 0, s11
	s_mul_i32 s11, s11, 0xc000
	s_mul_hi_u32 s14, s10, 0xc000
	s_add_i32 s14, s14, s11
	s_mul_i32 s10, s10, 0xc000
	s_add_u32 s10, s18, s10
	s_addc_u32 s11, s19, s14
	s_lshl_b64 s[14:15], s[16:17], 13
	v_lshl_add_u64 v[52:53], s[10:11], 0, v[34:35]
	s_mov_b64 s[10:11], 0x4000
	s_add_u32 s12, s12, s14
	v_lshl_add_u64 v[92:93], v[52:53], 0, s[10:11]
	s_movk_i32 s10, 0x5000
	s_addc_u32 s13, s13, s15
	v_add_co_u32_e32 v100, vcc, s10, v52
	s_lshl_b64 s[14:15], s[8:9], 12
	s_nop 0
	v_addc_co_u32_e32 v101, vcc, 0, v53, vcc
	s_mov_b64 s[10:11], 0x5000
	v_lshl_add_u64 v[104:105], s[12:13], 0, v[34:35]
	v_lshl_add_u64 v[50:51], v[32:33], 0, s[14:15]
	v_lshl_add_u64 v[28:29], v[52:53], 0, s[10:11]
	s_mov_b64 s[10:11], 0x5800
	v_add_co_u32_e32 v76, vcc, s61, v104
	global_load_dwordx4 v[0:3], v[50:51], off offset:3072
	global_load_dwordx4 v[4:7], v[50:51], off offset:2048
	v_lshl_add_u64 v[12:13], v[52:53], 0, s[10:11]
	v_lshl_add_u64 v[64:65], v[104:105], 0, s[22:23]
	v_addc_co_u32_e32 v77, vcc, 0, v105, vcc
	global_load_dwordx4 v[8:11], v[50:51], off offset:1024
	s_nop 0
	global_load_dwordx4 v[12:15], v[12:13], off offset:16
	s_nop 0
	global_load_dwordx4 v[16:19], v[100:101], off
	global_load_dwordx4 v[20:23], v[100:101], off offset:2048
	global_load_dwordx4 v[24:27], v[92:93], off offset:2064
	s_nop 0
	global_load_dwordx4 v[28:31], v[28:29], off offset:16
	s_mov_b64 s[10:11], 0x1000
	global_load_dwordx4 v[64:67], v[64:65], off offset:16
	v_lshl_add_u64 v[72:73], v[104:105], 0, s[10:11]
	global_load_dwordx4 v[68:71], v[76:77], off offset:2048
	global_load_dwordx4 v[60:63], v[92:93], off offset:2048
	s_nop 0
	global_load_dwordx4 v[72:75], v[72:73], off offset:16
	s_nop 0
	global_load_dwordx4 v[76:79], v[76:77], off
	s_nop 0
	global_load_dwordx4 v[80:83], v[104:105], off offset:2064
	global_load_dwordx4 v[84:87], v[104:105], off offset:2048
	global_load_dwordx4 v[88:91], v[50:51], off
	s_nop 0
	global_load_dwordx4 v[92:95], v[92:93], off offset:16
	s_nop 0
	global_load_dwordx4 v[96:99], v[104:105], off offset:16
	s_nop 0
	global_load_dwordx4 v[100:103], v[100:101], off offset:-4096
	s_nop 0
	global_load_dwordx4 v[104:107], v[104:105], off
	s_mov_b32 s10, 0x3fb504f3
	s_lshl_b64 s[8:9], s[8:9], 13
	s_add_u32 s4, s4, s20
	s_addc_u32 s5, s5, s21
	v_readlane_b32 s15, v254, 35
	s_cmp_lt_i32 s4, s15
	s_waitcnt vmcnt(19)
	v_lshlrev_b32_e32 v110, 16, v0
	v_and_b32_e32 v111, 0xffff0000, v0
	v_lshlrev_b32_e32 v0, 16, v1
	v_and_b32_e32 v1, 0xffff0000, v1
	s_waitcnt vmcnt(18)
	v_lshlrev_b32_e32 v114, 16, v4
	v_and_b32_e32 v115, 0xffff0000, v4
	s_waitcnt vmcnt(14)
	v_pk_mul_f32 v[0:1], v[22:23], v[0:1]
	v_pk_mul_f32 v[16:17], v[16:17], v[114:115]
	v_lshlrev_b32_e32 v108, 16, v2
	v_and_b32_e32 v109, 0xffff0000, v2
	v_lshlrev_b32_e32 v2, 16, v3
	s_waitcnt vmcnt(10)
	v_pk_fma_f32 v[114:115], v[70:71], s[10:11], v[0:1] op_sel_hi:[1,0,1]
	v_lshlrev_b32_e32 v0, 16, v9
	v_and_b32_e32 v1, 0xffff0000, v9
	s_waitcnt vmcnt(9)
	v_pk_mul_f32 v[0:1], v[62:63], v[0:1]
	v_and_b32_e32 v3, 0xffff0000, v3
	s_waitcnt vmcnt(5)
	v_pk_fma_f32 v[132:133], v[86:87], s[10:11], v[0:1] op_sel_hi:[1,0,1]
	s_waitcnt vmcnt(4)
	v_lshlrev_b32_e32 v0, 16, v90
	v_and_b32_e32 v1, 0xffff0000, v90
	s_waitcnt vmcnt(3)
	v_pk_mul_f32 v[0:1], v[92:93], v[0:1]
	v_pk_mul_f32 v[2:3], v[14:15], v[2:3]
	s_waitcnt vmcnt(2)
	v_pk_fma_f32 v[92:93], v[96:97], s[10:11], v[0:1] op_sel_hi:[1,0,1]
	v_lshlrev_b32_e32 v0, 16, v91
	v_and_b32_e32 v1, 0xffff0000, v91
	v_pk_mul_f32 v[0:1], v[94:95], v[0:1]
	v_pk_mul_f32 v[14:15], v[20:21], v[110:111]
	v_pk_fma_f32 v[94:95], v[98:99], s[10:11], v[0:1] op_sel_hi:[1,0,1]
	v_lshlrev_b32_e32 v0, 16, v88
	v_and_b32_e32 v1, 0xffff0000, v88
	s_waitcnt vmcnt(1)
	v_pk_mul_f32 v[0:1], v[100:101], v[0:1]
	v_pk_fma_f32 v[110:111], v[66:67], s[10:11], v[2:3] op_sel_hi:[1,0,1]
	s_waitcnt vmcnt(0)
	v_pk_fma_f32 v[96:97], v[104:105], s[10:11], v[0:1] op_sel_hi:[1,0,1]
	v_and_b32_e32 v1, 0xffff0000, v89
	v_add_f32_e32 v0, 0, v96
	v_add_f32_e32 v2, v97, v0
	v_lshlrev_b32_e32 v0, 16, v89
	v_pk_mul_f32 v[0:1], v[102:103], v[0:1]
	v_lshlrev_b32_e32 v118, 16, v8
	v_pk_fma_f32 v[98:99], v[106:107], s[10:11], v[0:1] op_sel_hi:[1,0,1]
	v_and_b32_e32 v119, 0xffff0000, v8
	v_add_f32_e32 v0, v98, v2
	v_add_f32_e32 v0, v99, v0
	v_add_f32_e32 v0, v92, v0
	v_add_f32_e32 v0, v93, v0
	v_pk_mul_f32 v[22:23], v[60:61], v[118:119]
	v_add_f32_e32 v0, v94, v0
	v_pk_fma_f32 v[130:131], v[84:85], s[10:11], v[22:23] op_sel_hi:[1,0,1]
	v_add_f32_e32 v0, v95, v0
	v_add_f32_e32 v0, v130, v0
	v_lshlrev_b32_e32 v4, 16, v5
	v_and_b32_e32 v5, 0xffff0000, v5
	v_lshlrev_b32_e32 v116, 16, v10
	v_and_b32_e32 v117, 0xffff0000, v10
	v_add_f32_e32 v0, v131, v0
	v_pk_mul_f32 v[4:5], v[18:19], v[4:5]
	v_pk_mul_f32 v[18:19], v[24:25], v[116:117]
	v_add_f32_e32 v0, v132, v0
	v_lshlrev_b32_e32 v10, 16, v11
	v_and_b32_e32 v11, 0xffff0000, v11
	v_pk_fma_f32 v[124:125], v[80:81], s[10:11], v[18:19] op_sel_hi:[1,0,1]
	v_add_f32_e32 v0, v133, v0
	v_pk_mul_f32 v[10:11], v[26:27], v[10:11]
	v_add_f32_e32 v0, v124, v0
	v_pk_fma_f32 v[126:127], v[82:83], s[10:11], v[10:11] op_sel_hi:[1,0,1]
	v_add_f32_e32 v0, v125, v0
	v_add_f32_e32 v0, v126, v0
	v_pk_fma_f32 v[120:121], v[76:77], s[10:11], v[16:17] op_sel_hi:[1,0,1]
	v_add_f32_e32 v0, v127, v0
	v_add_f32_e32 v0, v120, v0
	v_lshlrev_b32_e32 v112, 16, v6
	v_and_b32_e32 v113, 0xffff0000, v6
	v_pk_fma_f32 v[122:123], v[78:79], s[10:11], v[4:5] op_sel_hi:[1,0,1]
	v_add_f32_e32 v0, v121, v0
	v_pk_mul_f32 v[20:21], v[28:29], v[112:113]
	v_add_f32_e32 v0, v122, v0
	v_lshlrev_b32_e32 v6, 16, v7
	v_and_b32_e32 v7, 0xffff0000, v7
	v_pk_fma_f32 v[116:117], v[72:73], s[10:11], v[20:21] op_sel_hi:[1,0,1]
	v_add_f32_e32 v0, v123, v0
	v_pk_mul_f32 v[6:7], v[30:31], v[6:7]
	v_add_f32_e32 v0, v116, v0
	v_pk_fma_f32 v[118:119], v[74:75], s[10:11], v[6:7] op_sel_hi:[1,0,1]
	v_add_f32_e32 v0, v117, v0
	v_add_f32_e32 v0, v118, v0
	v_pk_fma_f32 v[112:113], v[68:69], s[10:11], v[14:15] op_sel_hi:[1,0,1]
	v_add_f32_e32 v0, v119, v0
	v_add_f32_e32 v0, v112, v0
	v_add_f32_e32 v0, v113, v0
	v_pk_mul_f32 v[12:13], v[12:13], v[108:109]
	v_add_f32_e32 v0, v114, v0
	v_pk_fma_f32 v[108:109], v[64:65], s[10:11], v[12:13] op_sel_hi:[1,0,1]
	v_add_f32_e32 v0, v115, v0
	v_add_f32_e32 v0, v108, v0
	v_add_f32_e32 v0, v109, v0
	v_add_f32_e32 v0, v110, v0
	v_add_f32_e32 v0, v111, v0
	s_mov_b32 s10, 0x800000
	s_waitcnt lgkmcnt(0)
; DI float wave_sum(float v) {
; #pragma unroll
;     for (int o = 1; o < 64; o <<= 1) v += __shfl_xor(v, o);
;     return v;
; DI void row_normalize(float (&v)[32]) {
;     float s = 0.f;
; #pragma unroll
;     for (int i = 0; i < 32; ++i) s += v[i];
;     const float mean = wave_sum(s) * (1.0f / D);
;     float q = 0.f;
; #pragma unroll
;     for (int i = 0; i < 32; ++i) { v[i] -= mean; q += v[i] * v[i]; }
;     const float rstd = rsqrtf(wave_sum(q) * (1.0f / D) + LN_EPS);
	s_nop 1
	v_add_f32_dpp v0, v0, v0 quad_perm:[1,0,3,2] row_mask:0xf bank_mask:0xf bound_ctrl:1
	s_waitcnt lgkmcnt(0)
	s_nop 1
	v_add_f32_dpp v8, v0, v0 quad_perm:[2,3,0,1] row_mask:0xf bank_mask:0xf bound_ctrl:1
	global_load_dwordx4 v[4:7], v[36:37], off offset:16
	global_load_dwordx4 v[0:3], v[36:37], off
	global_load_dwordx4 v[12:15], v[36:37], off offset:2064
	global_load_dwordx4 v[16:19], v[36:37], off offset:2048
	global_load_dwordx4 v[20:23], v[38:39], off offset:16
	global_load_dwordx4 v[24:27], v[38:39], off
	global_load_dwordx4 v[28:31], v[40:41], off offset:16
	global_load_dwordx4 v[60:63], v[40:41], off
	s_waitcnt lgkmcnt(0)
	s_nop 1
	v_add_f32_dpp v8, v8, v8 row_half_mirror row_mask:0xf bank_mask:0xf bound_ctrl:1
	s_waitcnt lgkmcnt(0)
	s_nop 1
	v_add_f32_dpp v76, v8, v8 row_mirror row_mask:0xf bank_mask:0xf bound_ctrl:1
	global_load_dwordx4 v[8:11], v[42:43], off offset:16
	global_load_dwordx4 v[64:67], v[42:43], off
	global_load_dwordx4 v[68:71], v[42:43], off offset:2064
	global_load_dwordx4 v[72:75], v[42:43], off offset:2048
	s_waitcnt lgkmcnt(0)
	v_mov_b32_e32 v77, v76
	v_mov_b32_e32 v100, v76
	s_nop 1
	v_permlane16_swap_b32_e32 v100, v77
	s_nop 1
	v_add_f32_e32 v100, v100, v77
	global_load_dwordx4 v[76:79], v[44:45], off offset:16
	global_load_dwordx4 v[80:83], v[44:45], off
	global_load_dwordx4 v[84:87], v[46:47], off offset:16
	global_load_dwordx4 v[88:91], v[46:47], off
	s_waitcnt lgkmcnt(0)
	v_mov_b32_e32 v101, v100
	s_nop 1
	v_permlane32_swap_b32_e32 v100, v101
	s_nop 1
	v_add_f32_e32 v100, v100, v101
	v_mul_f32_e32 v100, 0x3a000000, v100
	v_pk_add_f32 v[96:97], v[96:97], v[100:101] op_sel_hi:[1,0] neg_lo:[0,1] neg_hi:[0,1]
	v_pk_add_f32 v[98:99], v[98:99], v[100:101] op_sel_hi:[1,0] neg_lo:[0,1] neg_hi:[0,1]
	v_pk_mul_f32 v[102:103], v[96:97], v[96:97]
	v_pk_mul_f32 v[104:105], v[98:99], v[98:99]
	v_add_f32_e32 v102, v102, v103
	v_pk_add_f32 v[92:93], v[92:93], v[100:101] op_sel_hi:[1,0] neg_lo:[0,1] neg_hi:[0,1]
	v_add_f32_e32 v102, v104, v102
	v_pk_mul_f32 v[106:107], v[92:93], v[92:93]
	v_add_f32_e32 v102, v105, v102
	v_pk_add_f32 v[94:95], v[94:95], v[100:101] op_sel_hi:[1,0] neg_lo:[0,1] neg_hi:[0,1]
	v_add_f32_e32 v102, v106, v102
	v_pk_mul_f32 v[134:135], v[94:95], v[94:95]
	v_add_f32_e32 v102, v107, v102
	v_pk_add_f32 v[130:131], v[130:131], v[100:101] op_sel_hi:[1,0] neg_lo:[0,1] neg_hi:[0,1]
	v_add_f32_e32 v102, v134, v102
	v_pk_mul_f32 v[136:137], v[130:131], v[130:131]
	v_add_f32_e32 v102, v135, v102
	v_pk_add_f32 v[132:133], v[132:133], v[100:101] op_sel_hi:[1,0] neg_lo:[0,1] neg_hi:[0,1]
	v_add_f32_e32 v102, v136, v102
	v_pk_mul_f32 v[138:139], v[132:133], v[132:133]
	v_add_f32_e32 v102, v137, v102
	v_pk_add_f32 v[124:125], v[124:125], v[100:101] op_sel_hi:[1,0] neg_lo:[0,1] neg_hi:[0,1]
	v_add_f32_e32 v102, v138, v102
	v_pk_mul_f32 v[140:141], v[124:125], v[124:125]
	v_add_f32_e32 v102, v139, v102
	v_pk_add_f32 v[126:127], v[126:127], v[100:101] op_sel_hi:[1,0] neg_lo:[0,1] neg_hi:[0,1]
	v_add_f32_e32 v102, v140, v102
	v_pk_mul_f32 v[142:143], v[126:127], v[126:127]
	v_add_f32_e32 v102, v141, v102
	v_pk_add_f32 v[120:121], v[120:121], v[100:101] op_sel_hi:[1,0] neg_lo:[0,1] neg_hi:[0,1]
	v_add_f32_e32 v102, v142, v102
	v_pk_mul_f32 v[144:145], v[120:121], v[120:121]
	v_add_f32_e32 v102, v143, v102
	v_pk_add_f32 v[122:123], v[122:123], v[100:101] op_sel_hi:[1,0] neg_lo:[0,1] neg_hi:[0,1]
	v_add_f32_e32 v102, v144, v102
	v_pk_mul_f32 v[146:147], v[122:123], v[122:123]
	v_add_f32_e32 v102, v145, v102
	v_pk_add_f32 v[116:117], v[116:117], v[100:101] op_sel_hi:[1,0] neg_lo:[0,1] neg_hi:[0,1]
	v_add_f32_e32 v102, v146, v102
	v_pk_mul_f32 v[148:149], v[116:117], v[116:117]
	v_add_f32_e32 v102, v147, v102
	v_pk_add_f32 v[118:119], v[118:119], v[100:101] op_sel_hi:[1,0] neg_lo:[0,1] neg_hi:[0,1]
	v_add_f32_e32 v102, v148, v102
	v_pk_mul_f32 v[150:151], v[118:119], v[118:119]
	v_add_f32_e32 v102, v149, v102
	v_pk_add_f32 v[112:113], v[112:113], v[100:101] op_sel_hi:[1,0] neg_lo:[0,1] neg_hi:[0,1]
	v_add_f32_e32 v102, v150, v102
	v_pk_mul_f32 v[152:153], v[112:113], v[112:113]
	v_add_f32_e32 v102, v151, v102
	v_pk_add_f32 v[114:115], v[114:115], v[100:101] op_sel_hi:[1,0] neg_lo:[0,1] neg_hi:[0,1]
	v_add_f32_e32 v102, v152, v102
	v_pk_mul_f32 v[154:155], v[114:115], v[114:115]
	v_add_f32_e32 v102, v153, v102
	v_pk_add_f32 v[108:109], v[108:109], v[100:101] op_sel_hi:[1,0] neg_lo:[0,1] neg_hi:[0,1]
	v_add_f32_e32 v102, v154, v102
	v_pk_mul_f32 v[156:157], v[108:109], v[108:109]
	v_add_f32_e32 v102, v155, v102
	v_pk_add_f32 v[100:101], v[110:111], v[100:101] op_sel_hi:[1,0] neg_lo:[0,1] neg_hi:[0,1]
	v_add_f32_e32 v102, v156, v102
	v_pk_mul_f32 v[110:111], v[100:101], v[100:101]
	v_add_f32_e32 v102, v157, v102
	v_add_f32_e32 v102, v110, v102
	v_add_f32_e32 v102, v111, v102
	s_waitcnt lgkmcnt(0)
	s_nop 1
	v_add_f32_dpp v102, v102, v102 quad_perm:[1,0,3,2] row_mask:0xf bank_mask:0xf bound_ctrl:1
	s_waitcnt lgkmcnt(0)
	s_nop 1
	v_add_f32_dpp v102, v102, v102 quad_perm:[2,3,0,1] row_mask:0xf bank_mask:0xf bound_ctrl:1
	s_waitcnt lgkmcnt(0)
	s_nop 1
	v_add_f32_dpp v102, v102, v102 row_half_mirror row_mask:0xf bank_mask:0xf bound_ctrl:1
	s_waitcnt lgkmcnt(0)
	s_nop 1
	v_add_f32_dpp v102, v102, v102 row_mirror row_mask:0xf bank_mask:0xf bound_ctrl:1
	s_waitcnt lgkmcnt(0)
	v_mov_b32_e32 v103, v102
	s_nop 1
	v_permlane16_swap_b32_e32 v102, v103
	s_nop 1
	v_add_f32_e32 v102, v102, v103
	s_waitcnt lgkmcnt(0)
; DI void row_normalize(float (&v)[32]) {
;     float s = 0.f;
; #pragma unroll
;     for (int i = 0; i < 32; ++i) s += v[i];
;     const float mean = wave_sum(s) * (1.0f / D);
; DI void phase_ln1(int l, int nrows, int wv) {
;     ...
;         row_normalize(v);
;         { float a[32], bb[32]; load_row_f32(lg, F.lane, a); load_row_f32(lbias, F.lane, bb);
; #pragma unroll
;           for (int i = 0; i < 32; ++i) v[i] = v[i] * a[i] + bb[i]; }
;         store_row_f32(F.X + (size_t)r * D, F.lane, v);
;         row_normalize(v);
	v_mov_b32_e32 v103, v102
	s_nop 1
	v_permlane32_swap_b32_e32 v102, v103
	s_nop 1
	v_add_f32_e32 v102, v102, v103
	v_fmamk_f32 v102, v102, 0x3a000000, v206
	v_mul_f32_e32 v103, 0x4b800000, v102
	v_cmp_gt_f32_e32 vcc, s10, v102
	s_nop 1
	v_cndmask_b32_e32 v102, v102, v103, vcc
	v_rsq_f32_e32 v102, v102
	s_nop 0
	v_mul_f32_e32 v103, 0x45800000, v102
	v_cndmask_b32_e32 v102, v102, v103, vcc
	v_pk_mul_f32 v[96:97], v[96:97], v[102:103] op_sel_hi:[1,0]
	v_pk_mul_f32 v[92:93], v[92:93], v[102:103] op_sel_hi:[1,0]
	v_pk_mul_f32 v[104:105], v[130:131], v[102:103] op_sel_hi:[1,0]
	v_pk_mul_f32 v[120:121], v[120:121], v[102:103] op_sel_hi:[1,0]
	v_pk_mul_f32 v[112:113], v[112:113], v[102:103] op_sel_hi:[1,0]
	s_waitcnt vmcnt(6)
	v_pk_fma_f32 v[0:1], v[0:1], v[96:97], v[64:65]
	v_pk_mul_f32 v[98:99], v[98:99], v[102:103] op_sel_hi:[1,0]
	v_pk_fma_f32 v[8:9], v[4:5], v[92:93], v[8:9]
	s_waitcnt vmcnt(4)
	v_pk_fma_f32 v[4:5], v[16:17], v[104:105], v[72:73]
	s_waitcnt vmcnt(2)
	v_pk_fma_f32 v[16:17], v[24:25], v[120:121], v[80:81]
	s_waitcnt vmcnt(0)
	v_pk_fma_f32 v[24:25], v[60:61], v[112:113], v[88:89]
	v_add_f32_e32 v60, 0, v0
	v_pk_fma_f32 v[2:3], v[2:3], v[98:99], v[66:67]
	v_add_f32_e32 v60, v1, v60
	v_add_f32_e32 v60, v2, v60
	v_add_f32_e32 v60, v3, v60
	v_pk_mul_f32 v[94:95], v[94:95], v[102:103] op_sel_hi:[1,0]
	v_add_f32_e32 v60, v8, v60
	v_pk_fma_f32 v[10:11], v[6:7], v[94:95], v[10:11]
	v_add_f32_e32 v60, v9, v60
	v_add_f32_e32 v60, v10, v60
	v_add_f32_e32 v60, v11, v60
	v_pk_mul_f32 v[106:107], v[132:133], v[102:103] op_sel_hi:[1,0]
	v_add_f32_e32 v60, v4, v60
	v_pk_fma_f32 v[6:7], v[18:19], v[106:107], v[74:75]
	v_add_f32_e32 v60, v5, v60
	v_pk_mul_f32 v[110:111], v[124:125], v[102:103] op_sel_hi:[1,0]
	v_add_f32_e32 v60, v6, v60
	v_pk_fma_f32 v[12:13], v[12:13], v[110:111], v[68:69]
	v_add_f32_e32 v60, v7, v60
	v_pk_mul_f32 v[124:125], v[126:127], v[102:103] op_sel_hi:[1,0]
	v_add_f32_e32 v60, v12, v60
	v_pk_fma_f32 v[14:15], v[14:15], v[124:125], v[70:71]
	v_add_f32_e32 v60, v13, v60
	v_add_f32_e32 v60, v14, v60
	v_add_f32_e32 v60, v15, v60
	v_pk_mul_f32 v[122:123], v[122:123], v[102:103] op_sel_hi:[1,0]
	v_add_f32_e32 v60, v16, v60
	v_pk_fma_f32 v[18:19], v[26:27], v[122:123], v[82:83]
	v_add_f32_e32 v60, v17, v60
	v_pk_mul_f32 v[116:117], v[116:117], v[102:103] op_sel_hi:[1,0]
	v_add_f32_e32 v60, v18, v60
	v_pk_fma_f32 v[20:21], v[20:21], v[116:117], v[76:77]
	v_add_f32_e32 v60, v19, v60
	v_pk_mul_f32 v[118:119], v[118:119], v[102:103] op_sel_hi:[1,0]
	v_add_f32_e32 v60, v20, v60
	v_pk_fma_f32 v[22:23], v[22:23], v[118:119], v[78:79]
	v_add_f32_e32 v60, v21, v60
	v_add_f32_e32 v60, v22, v60
	v_add_f32_e32 v60, v23, v60
	v_pk_mul_f32 v[114:115], v[114:115], v[102:103] op_sel_hi:[1,0]
	v_add_f32_e32 v60, v24, v60
	v_pk_fma_f32 v[26:27], v[62:63], v[114:115], v[90:91]
	v_add_f32_e32 v60, v25, v60
	v_pk_mul_f32 v[108:109], v[108:109], v[102:103] op_sel_hi:[1,0]
	v_add_f32_e32 v60, v26, v60
	v_pk_fma_f32 v[28:29], v[28:29], v[108:109], v[84:85]
	v_add_f32_e32 v60, v27, v60
	v_pk_mul_f32 v[100:101], v[100:101], v[102:103] op_sel_hi:[1,0]
	v_add_f32_e32 v60, v28, v60
	v_pk_fma_f32 v[30:31], v[30:31], v[100:101], v[86:87]
	v_add_f32_e32 v60, v29, v60
	v_add_f32_e32 v60, v30, v60
	v_add_f32_e32 v60, v31, v60
	s_waitcnt lgkmcnt(0)
	s_nop 1
	v_add_f32_dpp v60, v60, v60 quad_perm:[1,0,3,2] row_mask:0xf bank_mask:0xf bound_ctrl:1
	s_waitcnt lgkmcnt(0)
	s_nop 1
	v_add_f32_dpp v60, v60, v60 quad_perm:[2,3,0,1] row_mask:0xf bank_mask:0xf bound_ctrl:1
	s_waitcnt lgkmcnt(0)
	s_nop 1
	v_add_f32_dpp v62, v60, v60 row_half_mirror row_mask:0xf bank_mask:0xf bound_ctrl:1
	v_lshl_add_u64 v[60:61], v[48:49], 0, s[8:9]
	v_add_co_u32_e32 v96, vcc, s61, v60
	global_store_dwordx4 v[60:61], v[0:3], off
	global_store_dwordx4 v[60:61], v[8:11], off offset:16
	global_store_dwordx4 v[60:61], v[4:7], off offset:2048
	global_store_dwordx4 v[60:61], v[12:15], off offset:2064
	s_waitcnt lgkmcnt(0)
	s_nop 1
	v_add_f32_dpp v62, v62, v62 row_mirror row_mask:0xf bank_mask:0xf bound_ctrl:1
	v_addc_co_u32_e32 v97, vcc, 0, v61, vcc
	global_store_dwordx4 v[96:97], v[16:19], off
	global_store_dwordx4 v[96:97], v[20:23], off offset:16
	global_store_dwordx4 v[96:97], v[24:27], off offset:2048
	s_movk_i32 s8, 0x7000
	s_waitcnt lgkmcnt(0)
	v_mov_b32_e32 v63, v62
	s_nop 1
	v_permlane16_swap_b32_e32 v62, v63
	s_nop 1
	v_add_f32_e32 v62, v62, v63
	v_add_co_u32_e32 v98, vcc, s8, v52
	s_mov_b32 s8, 0x9000
	s_nop 0
	v_addc_co_u32_e32 v99, vcc, 0, v53, vcc
	s_waitcnt lgkmcnt(0)
; DI void row_normalize(float (&v)[32]) {
;     float s = 0.f;
; #pragma unroll
;     for (int i = 0; i < 32; ++i) s += v[i];
;     const float mean = wave_sum(s) * (1.0f / D);
;     float q = 0.f;
; #pragma unroll
;     for (int i = 0; i < 32; ++i) { v[i] -= mean; q += v[i] * v[i]; }
;     const float rstd = rsqrtf(wave_sum(q) * (1.0f / D) + LN_EPS);
; DI void phase_ln1(int l, int nrows, int wv) {
;     ...
;         row_normalize(v);
;         { float sh[32], sc[32]; load_row_f32(md + 3 * D, F.lane, sh); load_row_f32(md + 4 * D, F.lane, sc);
	v_mov_b32_e32 v63, v62
	v_mov_b32_e32 v61, v62
	s_nop 1
	v_permlane32_swap_b32_e32 v61, v63
	s_nop 1
	v_add_f32_e32 v61, v61, v63
	v_fmac_f32_e32 v1, 0xba000000, v61
	v_fmamk_f32 v0, v61, 0xba000000, v0
	v_mul_f32_e32 v64, v1, v1
	v_fmac_f32_e32 v64, v0, v0
	v_fmamk_f32 v2, v61, 0xba000000, v2
	v_fmac_f32_e32 v64, v2, v2
	v_fmac_f32_e32 v3, 0xba000000, v61
	v_fmac_f32_e32 v64, v3, v3
	v_fmamk_f32 v8, v61, 0xba000000, v8
	v_fmac_f32_e32 v64, v8, v8
	v_fmac_f32_e32 v9, 0xba000000, v61
	v_fmac_f32_e32 v64, v9, v9
	v_fmamk_f32 v10, v61, 0xba000000, v10
	v_fmac_f32_e32 v64, v10, v10
	v_fmac_f32_e32 v11, 0xba000000, v61
	v_fmac_f32_e32 v64, v11, v11
	v_fmamk_f32 v4, v61, 0xba000000, v4
	v_fmac_f32_e32 v64, v4, v4
	v_fmac_f32_e32 v5, 0xba000000, v61
	v_fmac_f32_e32 v64, v5, v5
	v_fmamk_f32 v6, v61, 0xba000000, v6
	v_fmac_f32_e32 v64, v6, v6
	v_fmac_f32_e32 v7, 0xba000000, v61
	v_fmac_f32_e32 v64, v7, v7
	v_fmamk_f32 v12, v61, 0xba000000, v12
	v_fmac_f32_e32 v64, v12, v12
	v_fmac_f32_e32 v13, 0xba000000, v61
	v_fmac_f32_e32 v64, v13, v13
	v_fmamk_f32 v14, v61, 0xba000000, v14
	v_fmac_f32_e32 v64, v14, v14
	v_fmac_f32_e32 v15, 0xba000000, v61
	v_fmac_f32_e32 v64, v15, v15
	v_fmamk_f32 v16, v61, 0xba000000, v16
	v_fmac_f32_e32 v64, v16, v16
	v_fmac_f32_e32 v17, 0xba000000, v61
	v_fmac_f32_e32 v64, v17, v17
	v_fmamk_f32 v18, v61, 0xba000000, v18
	v_fmac_f32_e32 v64, v18, v18
	v_fmac_f32_e32 v19, 0xba000000, v61
	v_fmac_f32_e32 v64, v19, v19
	v_fmamk_f32 v20, v61, 0xba000000, v20
	v_fmac_f32_e32 v64, v20, v20
	v_fmac_f32_e32 v21, 0xba000000, v61
	v_fmac_f32_e32 v64, v21, v21
	v_fmamk_f32 v22, v61, 0xba000000, v22
	v_fmac_f32_e32 v64, v22, v22
	v_fmac_f32_e32 v23, 0xba000000, v61
	v_fmac_f32_e32 v64, v23, v23
	v_fmamk_f32 v24, v61, 0xba000000, v24
	v_fmac_f32_e32 v64, v24, v24
	v_fmac_f32_e32 v25, 0xba000000, v61
	v_mul_f32_e32 v60, 0x3a000000, v61
	v_fmac_f32_e32 v64, v25, v25
	v_fmamk_f32 v26, v61, 0xba000000, v26
	v_fmac_f32_e32 v64, v26, v26
	v_fmac_f32_e32 v27, 0xba000000, v61
	v_pk_add_f32 v[116:117], v[28:29], v[60:61] op_sel_hi:[1,0] neg_lo:[0,1] neg_hi:[0,1]
	v_fmac_f32_e32 v64, v27, v27
	v_pk_mul_f32 v[62:63], v[116:117], v[116:117]
	v_add_co_u32_e32 v112, vcc, s8, v52
	v_add_f32_e32 v61, v62, v64
	v_pk_add_f32 v[118:119], v[30:31], v[60:61] op_sel_hi:[1,0] neg_lo:[0,1] neg_hi:[0,1]
	v_add_f32_e32 v62, v63, v61
	v_pk_mul_f32 v[60:61], v[118:119], v[118:119]
	s_mov_b64 s[8:9], 0x6000
	v_add_f32_e32 v60, v60, v62
	v_add_f32_e32 v60, v61, v60
	v_addc_co_u32_e32 v113, vcc, 0, v53, vcc
	v_lshl_add_u64 v[88:89], v[52:53], 0, s[8:9]
	s_mov_b64 s[8:9], 0x8000
	s_waitcnt lgkmcnt(0)
	s_nop 1
	v_add_f32_dpp v60, v60, v60 quad_perm:[1,0,3,2] row_mask:0xf bank_mask:0xf bound_ctrl:1
	v_lshl_add_u64 v[84:85], v[52:53], 0, s[8:9]
	s_mov_b64 s[8:9], 0x7000
	s_waitcnt lgkmcnt(0)
	s_nop 1
	v_add_f32_dpp v68, v60, v60 quad_perm:[2,3,0,1] row_mask:0xf bank_mask:0xf bound_ctrl:1
	global_load_dwordx4 v[60:63], v[112:113], off offset:-4096
	global_load_dwordx4 v[64:67], v[98:99], off offset:-4096
	s_waitcnt lgkmcnt(0)
	s_nop 1
	v_add_f32_dpp v76, v68, v68 row_half_mirror row_mask:0xf bank_mask:0xf bound_ctrl:1
	global_load_dwordx4 v[68:71], v[84:85], off offset:16
	global_load_dwordx4 v[72:75], v[88:89], off offset:16
	s_waitcnt lgkmcnt(0)
	s_nop 1
	v_add_f32_dpp v90, v76, v76 row_mirror row_mask:0xf bank_mask:0xf bound_ctrl:1
	global_load_dwordx4 v[76:79], v[84:85], off offset:2048
	global_load_dwordx4 v[80:83], v[88:89], off offset:2048
	s_waitcnt lgkmcnt(0)
	v_mov_b32_e32 v91, v90
	v_mov_b32_e32 v100, v90
	s_nop 1
	v_permlane16_swap_b32_e32 v100, v91
	s_nop 1
	v_add_f32_e32 v100, v100, v91
	global_load_dwordx4 v[84:87], v[84:85], off offset:2064
	s_nop 0
	global_load_dwordx4 v[88:91], v[88:89], off offset:2064
	s_nop 0
	global_load_dwordx4 v[92:95], v[98:99], off offset:2048
	s_waitcnt vmcnt(8)
	v_add_f32_e32 v63, 1.0, v63
	global_store_dwordx4 v[96:97], v[28:31], off offset:2064
	v_add_f32_e32 v60, 1.0, v60
	v_add_f32_e32 v61, 1.0, v61
	s_waitcnt lgkmcnt(0)
; DI void row_normalize(float (&v)[32]) {
;     ...
;     const float rstd = rsqrtf(wave_sum(q) * (1.0f / D) + LN_EPS);
; #pragma unroll
;     for (int i = 0; i < 32; ++i) v[i] *= rstd;
; DI void phase_ln1(int l, int nrows, int wv) {
;     ...
;         { float sh[32], sc[32]; load_row_f32(md + 3 * D, F.lane, sh); load_row_f32(md + 4 * D, F.lane, sc);
; #pragma unroll
;           for (int i = 0; i < 32; ++i) v[i] = v[i] * (1.0f + sc[i]) + sh[i]; }
;         store_row_bf16(F.H + (size_t)r * D, F.lane, v);
	v_mov_b32_e32 v101, v100
	v_mov_b32_e32 v28, v100
	s_nop 1
	v_permlane32_swap_b32_e32 v28, v101
	s_nop 1
	v_add_f32_e32 v28, v28, v101
	v_fmamk_f32 v100, v28, 0x3a000000, v206
	v_mul_f32_e32 v101, 0x4b800000, v100
	v_cmp_gt_f32_e32 vcc, s10, v100
	global_load_dwordx4 v[28:31], v[112:113], off
	s_nop 0
	global_load_dwordx4 v[96:99], v[98:99], off
	v_cndmask_b32_e32 v100, v100, v101, vcc
	v_rsq_f32_e32 v114, v100
	v_lshl_add_u64 v[100:101], v[52:53], 0, s[8:9]
	s_mov_b64 s[8:9], 0x9000
	v_lshl_add_u64 v[104:105], v[52:53], 0, s[8:9]
	s_mov_b64 s[8:9], 0x7800
	v_mul_f32_e32 v115, 0x45800000, v114
	v_lshl_add_u64 v[108:109], v[52:53], 0, s[8:9]
	v_cndmask_b32_e32 v120, v114, v115, vcc
	s_mov_b64 s[8:9], 0x9800
	global_load_dwordx4 v[104:107], v[104:105], off offset:16
	v_mul_f32_e32 v121, v0, v120
	v_mul_f32_e32 v122, v1, v120
	v_lshl_add_u64 v[0:1], v[52:53], 0, s[8:9]
	global_load_dwordx4 v[100:103], v[100:101], off offset:16
	v_mul_f32_e32 v123, v2, v120
	global_load_dwordx4 v[112:115], v[112:113], off offset:2048
	v_mul_f32_e32 v124, v3, v120
	global_load_dwordx4 v[0:3], v[0:1], off offset:16
	v_mul_f32_e32 v8, v8, v120
	global_load_dwordx4 v[108:111], v[108:109], off offset:16
	s_waitcnt vmcnt(15)
	v_fmac_f32_e32 v67, v63, v124
	s_waitcnt vmcnt(14)
	v_add_f32_e32 v63, 1.0, v68
	v_mul_f32_e32 v9, v9, v120
	s_waitcnt vmcnt(13)
	v_fma_f32 v8, v63, v8, v72
	v_add_f32_e32 v63, 1.0, v69
	v_mul_f32_e32 v10, v10, v120
	v_fma_f32 v9, v63, v9, v73
	v_add_f32_e32 v63, 1.0, v70
	v_mul_f32_e32 v11, v11, v120
	v_fma_f32 v10, v63, v10, v74
	v_add_f32_e32 v63, 1.0, v71
	v_mul_f32_e32 v4, v4, v120
	v_fmac_f32_e32 v75, v63, v11
	s_waitcnt vmcnt(12)
	v_add_f32_e32 v11, 1.0, v76
	v_mul_f32_e32 v5, v5, v120
	s_waitcnt vmcnt(11)
	v_fma_f32 v4, v11, v4, v80
	v_add_f32_e32 v11, 1.0, v77
	v_mul_f32_e32 v6, v6, v120
	v_fma_f32 v5, v11, v5, v81
	v_add_f32_e32 v11, 1.0, v78
	v_mul_f32_e32 v7, v7, v120
	v_fma_f32 v6, v11, v6, v82
	v_add_f32_e32 v11, 1.0, v79
	v_mul_f32_e32 v13, v13, v120
	v_fmac_f32_e32 v83, v11, v7
	s_waitcnt vmcnt(10)
	v_add_f32_e32 v11, 1.0, v85
	v_mul_f32_e32 v15, v15, v120
	s_waitcnt vmcnt(9)
	v_fma_f32 v11, v11, v13, v89
	v_add_f32_e32 v13, 1.0, v87
	v_mul_f32_e32 v18, v18, v120
	v_fmac_f32_e32 v91, v13, v15
	v_mul_f32_e32 v16, v16, v120
	v_mul_f32_e32 v22, v22, v120
	v_mul_f32_e32 v19, v19, v120
	v_mul_f32_e32 v27, v27, v120
	v_mul_f32_e32 v52, v116, v120
	v_mul_f32_e32 v23, v23, v120
	v_mul_f32_e32 v53, v117, v120
	v_mul_f32_e32 v12, v12, v120
	v_mul_f32_e32 v24, v24, v120
	v_mul_f32_e32 v116, v118, v120
	v_add_f32_e32 v7, 1.0, v84
	v_mul_f32_e32 v14, v14, v120
	v_mul_f32_e32 v117, v119, v120
	v_add_f32_e32 v62, 1.0, v62
	v_fma_f32 v7, v7, v12, v88
	v_add_f32_e32 v12, 1.0, v86
	v_mul_f32_e32 v17, v17, v120
	v_fma_f32 v60, v60, v121, v64
	v_fma_f32 v61, v61, v122, v65
	v_fma_f32 v62, v62, v123, v66
	v_fma_f32 v12, v12, v14, v90
	v_mul_f32_e32 v20, v20, v120
	v_mul_f32_e32 v21, v21, v120
	v_mul_f32_e32 v25, v25, v120
	v_mul_f32_e32 v26, v26, v120
	s_waitcnt vmcnt(6)
	v_add_f32_e32 v15, 1.0, v30
	v_add_f32_e32 v13, 1.0, v28
	s_waitcnt vmcnt(5)
	v_fma_f32 v15, v15, v18, v98
	v_fma_f32 v13, v13, v16, v96
	v_add_f32_e32 v16, 1.0, v31
	v_fmac_f32_e32 v99, v16, v19
	v_add_f32_e32 v14, 1.0, v29
	v_fma_f32 v14, v14, v17, v97
	s_waitcnt vmcnt(4)
	v_add_f32_e32 v18, 1.0, v106
	v_add_f32_e32 v19, 1.0, v107
	v_add_f32_e32 v16, 1.0, v104
	v_add_f32_e32 v17, 1.0, v105
	s_waitcnt vmcnt(3)
	v_fma_f32 v18, v18, v22, v102
	v_fmac_f32_e32 v103, v19, v23
	s_waitcnt vmcnt(2)
	v_add_f32_e32 v22, 1.0, v115
	v_fmac_f32_e32 v95, v22, v27
	s_waitcnt vmcnt(1)
	v_add_f32_e32 v0, 1.0, v0
	v_add_f32_e32 v19, 1.0, v112
	s_waitcnt vmcnt(0)
	v_fma_f32 v22, v0, v52, v108
	v_add_f32_e32 v0, 1.0, v1
	v_fma_f32 v23, v0, v53, v109
	v_add_f32_e32 v0, 1.0, v2
	v_fma_f32 v19, v19, v24, v92
	v_fma_f32 v24, v0, v116, v110
	v_add_f32_e32 v0, 1.0, v3
	v_fmac_f32_e32 v111, v0, v117
	v_cvt_pk_bf16_f32 v0, v60, v61
	v_cvt_pk_bf16_f32 v1, v62, v67
	v_cvt_pk_bf16_f32 v2, v8, v9
	v_cvt_pk_bf16_f32 v3, v10, v75
	global_store_dwordx4 v[50:51], v[0:3], off
	v_fma_f32 v16, v16, v20, v100
	v_fma_f32 v17, v17, v21, v101
	v_cvt_pk_bf16_f32 v0, v4, v5
	v_cvt_pk_bf16_f32 v1, v6, v83
	v_cvt_pk_bf16_f32 v2, v7, v11
	v_cvt_pk_bf16_f32 v3, v12, v91
	v_add_f32_e32 v20, 1.0, v113
	v_add_f32_e32 v21, 1.0, v114
	global_store_dwordx4 v[50:51], v[0:3], off offset:1024
	v_fma_f32 v20, v20, v25, v93
	v_fma_f32 v21, v21, v26, v94
	v_cvt_pk_bf16_f32 v0, v13, v14
	v_cvt_pk_bf16_f32 v1, v15, v99
	v_cvt_pk_bf16_f32 v2, v16, v17
	v_cvt_pk_bf16_f32 v3, v18, v103
	global_store_dwordx4 v[50:51], v[0:3], off offset:2048
	s_nop 1
	v_cvt_pk_bf16_f32 v0, v19, v20
	v_cvt_pk_bf16_f32 v1, v21, v95
	v_cvt_pk_bf16_f32 v2, v22, v23
	v_cvt_pk_bf16_f32 v3, v24, v111
	global_store_dwordx4 v[50:51], v[0:3], off offset:3072
	s_cbranch_scc0 .LBB0_781

; #define CBAR() asm volatile("" ::: "memory")
; DI void row_normalize(float (&v)[32]) {
;     float s = 0.f;
; #pragma unroll
;     for (int i = 0; i < 32; ++i) s += v[i];
;     const float mean = wave_sum(s) * (1.0f / D);
;     float q = 0.f;
; #pragma unroll
;     for (int i = 0; i < 32; ++i) { v[i] -= mean; q += v[i] * v[i]; }
;     const float rstd = rsqrtf(wave_sum(q) * (1.0f / D) + LN_EPS);
; DI void phase_peer_ln2(int l, int nrows, bool last, int wv) {
;     ...
;     for (int r = blockIdx.x * NWAVES + T.wave; r < nrows; r += T.G * NWAVES) {
;         float v[32];
;         load16_f32(T.X + (size_t)r * D, lane, v);
;         row_normalize(v);
;         { float t[32]; load16_f32(lg2, lane, t);
; #pragma unroll
;           for (int i = 0; i < 32; ++i) v[i] *= t[i]; }
;         CBAR();
;         { float t[32]; load16_f32(lb2, lane, t);
.LBB0_1152:
	v_lshl_add_u64 v[0:1], s[0:1], 0, v[94:95]
	v_add_co_u32_e32 v2, vcc, 0xcc00000, v0
	s_mov_b32 s3, 0xcc01000
	s_nop 0
	v_addc_co_u32_e32 v3, vcc, 0, v1, vcc
	global_load_dwordx4 v[102:105], v[2:3], off
	global_load_dwordx4 v[106:109], v[2:3], off offset:1024
	global_load_dwordx4 v[110:113], v[2:3], off offset:2048
	global_load_dwordx4 v[114:117], v[2:3], off offset:3072
	v_add_co_u32_e32 v0, vcc, s3, v0
	s_mov_b32 s3, 0x800000
	s_nop 0
	v_addc_co_u32_e32 v1, vcc, 0, v1, vcc
	global_load_dwordx4 v[118:121], v[0:1], off
	global_load_dwordx4 v[122:125], v[0:1], off offset:1024
	global_load_dwordx4 v[130:133], v[0:1], off offset:2048
	global_load_dwordx4 v[64:67], v[0:1], off offset:3072
	v_readlane_b32 s18, v254, 33
	v_readlane_b32 s19, v254, 34
	s_waitcnt vmcnt(7)
	v_add_f32_e32 v0, 0, v102
	v_add_f32_e32 v0, v103, v0
	v_add_f32_e32 v0, v104, v0
	v_add_f32_e32 v0, v105, v0
	s_waitcnt vmcnt(6)
	v_add_f32_e32 v0, v106, v0
	v_add_f32_e32 v0, v107, v0
	v_add_f32_e32 v0, v108, v0
	v_add_f32_e32 v0, v109, v0
	s_waitcnt vmcnt(5)
	v_add_f32_e32 v0, v110, v0
	v_add_f32_e32 v0, v111, v0
	v_add_f32_e32 v0, v112, v0
	v_add_f32_e32 v0, v113, v0
	s_waitcnt vmcnt(4)
	v_add_f32_e32 v0, v114, v0
	v_add_f32_e32 v0, v115, v0
	v_add_f32_e32 v0, v116, v0
	v_add_f32_e32 v0, v117, v0
	s_waitcnt vmcnt(3)
	v_add_f32_e32 v0, v118, v0
	v_add_f32_e32 v0, v119, v0
	v_add_f32_e32 v0, v120, v0
	v_add_f32_e32 v0, v121, v0
	s_waitcnt vmcnt(2)
	v_add_f32_e32 v0, v122, v0
	v_add_f32_e32 v0, v123, v0
	v_add_f32_e32 v0, v124, v0
	v_add_f32_e32 v0, v125, v0
	s_waitcnt vmcnt(1)
	v_add_f32_e32 v0, v130, v0
	v_add_f32_e32 v0, v131, v0
	v_add_f32_e32 v0, v132, v0
	v_add_f32_e32 v0, v133, v0
	s_waitcnt vmcnt(0)
	v_add_f32_e32 v0, v64, v0
	v_add_f32_e32 v0, v65, v0
	v_add_f32_e32 v0, v66, v0
	v_add_f32_e32 v0, v67, v0
	s_waitcnt lgkmcnt(0)
	s_nop 1
	v_add_f32_dpp v0, v0, v0 quad_perm:[1,0,3,2] row_mask:0xf bank_mask:0xf bound_ctrl:1
	s_waitcnt lgkmcnt(0)
	s_nop 1
	v_add_f32_dpp v0, v0, v0 quad_perm:[2,3,0,1] row_mask:0xf bank_mask:0xf bound_ctrl:1
	s_waitcnt lgkmcnt(0)
	s_nop 1
	v_add_f32_dpp v0, v0, v0 row_half_mirror row_mask:0xf bank_mask:0xf bound_ctrl:1
	s_waitcnt lgkmcnt(0)
	s_nop 1
	v_add_f32_dpp v0, v0, v0 row_mirror row_mask:0xf bank_mask:0xf bound_ctrl:1
	s_waitcnt lgkmcnt(0)
	v_mov_b32_e32 v1, v0
	s_nop 1
	v_permlane16_swap_b32_e32 v0, v1
	s_nop 1
	v_add_f32_e32 v0, v0, v1
	s_waitcnt lgkmcnt(0)
	v_mov_b32_e32 v1, v0
	s_nop 1
	v_permlane32_swap_b32_e32 v0, v1
	s_nop 1
	v_add_f32_e32 v0, v0, v1
	v_mul_f32_e32 v126, 0x3a000000, v0
	global_load_dwordx4 v[4:7], v[70:71], off
	global_load_dwordx4 v[12:15], v[70:71], off offset:1024
	global_load_dwordx4 v[8:11], v[70:71], off offset:2048
	global_load_dwordx4 v[0:3], v[70:71], off offset:3072
	global_load_dwordx4 v[36:39], v[72:73], off
	global_load_dwordx4 v[44:47], v[74:75], off
	global_load_dwordx4 v[40:43], v[76:77], off
	global_load_dwordx4 v[32:35], v[78:79], off
	global_load_dwordx4 v[28:31], v[80:81], off
	global_load_dwordx4 v[24:27], v[80:81], off offset:1024
	global_load_dwordx4 v[20:23], v[80:81], off offset:2048
	global_load_dwordx4 v[16:19], v[80:81], off offset:3072
	global_load_dwordx4 v[60:63], v[82:83], off
	global_load_dwordx4 v[56:59], v[84:85], off
	global_load_dwordx4 v[52:55], v[86:87], off
	global_load_dwordx4 v[48:51], v[88:89], off
	v_pk_add_f32 v[102:103], v[102:103], v[126:127] op_sel_hi:[1,0] neg_lo:[0,1] neg_hi:[0,1]
	v_pk_add_f32 v[104:105], v[104:105], v[126:127] op_sel_hi:[1,0] neg_lo:[0,1] neg_hi:[0,1]
	v_pk_mul_f32 v[134:135], v[102:103], v[102:103]
	v_pk_mul_f32 v[136:137], v[104:105], v[104:105]
	v_add_f32_e32 v128, v134, v135
	v_pk_add_f32 v[106:107], v[106:107], v[126:127] op_sel_hi:[1,0] neg_lo:[0,1] neg_hi:[0,1]
	v_add_f32_e32 v128, v136, v128
	v_pk_mul_f32 v[138:139], v[106:107], v[106:107]
	v_add_f32_e32 v128, v137, v128
	v_pk_add_f32 v[108:109], v[108:109], v[126:127] op_sel_hi:[1,0] neg_lo:[0,1] neg_hi:[0,1]
	v_add_f32_e32 v128, v138, v128
	v_pk_mul_f32 v[140:141], v[108:109], v[108:109]
	v_add_f32_e32 v128, v139, v128
	v_pk_add_f32 v[110:111], v[110:111], v[126:127] op_sel_hi:[1,0] neg_lo:[0,1] neg_hi:[0,1]
	v_add_f32_e32 v128, v140, v128
	v_pk_mul_f32 v[142:143], v[110:111], v[110:111]
	v_add_f32_e32 v128, v141, v128
	v_pk_add_f32 v[112:113], v[112:113], v[126:127] op_sel_hi:[1,0] neg_lo:[0,1] neg_hi:[0,1]
	v_add_f32_e32 v128, v142, v128
	v_pk_mul_f32 v[144:145], v[112:113], v[112:113]
	v_add_f32_e32 v128, v143, v128
	v_pk_add_f32 v[114:115], v[114:115], v[126:127] op_sel_hi:[1,0] neg_lo:[0,1] neg_hi:[0,1]
	v_add_f32_e32 v128, v144, v128
	v_pk_mul_f32 v[146:147], v[114:115], v[114:115]
	v_add_f32_e32 v128, v145, v128
	v_pk_add_f32 v[116:117], v[116:117], v[126:127] op_sel_hi:[1,0] neg_lo:[0,1] neg_hi:[0,1]
	v_add_f32_e32 v128, v146, v128
	v_pk_mul_f32 v[148:149], v[116:117], v[116:117]
	v_add_f32_e32 v128, v147, v128
	v_pk_add_f32 v[118:119], v[118:119], v[126:127] op_sel_hi:[1,0] neg_lo:[0,1] neg_hi:[0,1]
	v_add_f32_e32 v128, v148, v128
	v_pk_mul_f32 v[150:151], v[118:119], v[118:119]
	v_add_f32_e32 v128, v149, v128
	v_pk_add_f32 v[120:121], v[120:121], v[126:127] op_sel_hi:[1,0] neg_lo:[0,1] neg_hi:[0,1]
	v_add_f32_e32 v128, v150, v128
	v_pk_mul_f32 v[152:153], v[120:121], v[120:121]
	v_add_f32_e32 v128, v151, v128
	v_pk_add_f32 v[122:123], v[122:123], v[126:127] op_sel_hi:[1,0] neg_lo:[0,1] neg_hi:[0,1]
	v_add_f32_e32 v128, v152, v128
	v_pk_mul_f32 v[154:155], v[122:123], v[122:123]
	v_add_f32_e32 v128, v153, v128
	v_pk_add_f32 v[124:125], v[124:125], v[126:127] op_sel_hi:[1,0] neg_lo:[0,1] neg_hi:[0,1]
	v_add_f32_e32 v128, v154, v128
	v_pk_mul_f32 v[156:157], v[124:125], v[124:125]
	v_add_f32_e32 v128, v155, v128
	v_pk_add_f32 v[130:131], v[130:131], v[126:127] op_sel_hi:[1,0] neg_lo:[0,1] neg_hi:[0,1]
	v_add_f32_e32 v128, v156, v128
	v_pk_mul_f32 v[158:159], v[130:131], v[130:131]
	v_add_f32_e32 v128, v157, v128
	v_pk_add_f32 v[132:133], v[132:133], v[126:127] op_sel_hi:[1,0] neg_lo:[0,1] neg_hi:[0,1]
	v_add_f32_e32 v128, v158, v128
	v_pk_mul_f32 v[160:161], v[132:133], v[132:133]
	v_add_f32_e32 v128, v159, v128
	v_pk_add_f32 v[64:65], v[64:65], v[126:127] op_sel_hi:[1,0] neg_lo:[0,1] neg_hi:[0,1]
	v_add_f32_e32 v128, v160, v128
	v_pk_mul_f32 v[162:163], v[64:65], v[64:65]
	v_add_f32_e32 v128, v161, v128
	v_pk_add_f32 v[66:67], v[66:67], v[126:127] op_sel_hi:[1,0] neg_lo:[0,1] neg_hi:[0,1]
	v_add_f32_e32 v128, v162, v128
	v_pk_mul_f32 v[126:127], v[66:67], v[66:67]
	v_add_f32_e32 v128, v163, v128
	v_add_f32_e32 v126, v126, v128
	v_add_f32_e32 v126, v127, v126
	s_waitcnt lgkmcnt(0)
; #define CBAR() asm volatile("" ::: "memory")
; DI void row_normalize(float (&v)[32]) {
;     float s = 0.f;
; #pragma unroll
;     for (int i = 0; i < 32; ++i) s += v[i];
;     const float mean = wave_sum(s) * (1.0f / D);
; DI void phase_peer_ln2(int l, int nrows, bool last, int wv) {
;     ...
;         load16_f32(T.X + (size_t)r * D, lane, v);
;         row_normalize(v);
;         { float t[32]; load16_f32(lg2, lane, t);
; #pragma unroll
;           for (int i = 0; i < 32; ++i) v[i] *= t[i]; }
;         CBAR();
;         { float t[32]; load16_f32(lb2, lane, t);
; #pragma unroll
;           for (int i = 0; i < 32; ++i) v[i] += t[i]; }
;         CBAR();
;         store16_f32(last ? T.out + (size_t)r * D : T.X + (size_t)r * D, lane, v);
;         if (!last) {
;             const float* mdn = T.mod + ((size_t)(l + 1) * 9 + modrow(r)) * MODW;
;             row_normalize(v);
	s_nop 1
	v_add_f32_dpp v126, v126, v126 quad_perm:[1,0,3,2] row_mask:0xf bank_mask:0xf bound_ctrl:1
	s_waitcnt lgkmcnt(0)
	s_nop 1
	v_add_f32_dpp v126, v126, v126 quad_perm:[2,3,0,1] row_mask:0xf bank_mask:0xf bound_ctrl:1
	s_waitcnt lgkmcnt(0)
	s_nop 1
	v_add_f32_dpp v126, v126, v126 row_half_mirror row_mask:0xf bank_mask:0xf bound_ctrl:1
	s_waitcnt lgkmcnt(0)
	s_nop 1
	v_add_f32_dpp v126, v126, v126 row_mirror row_mask:0xf bank_mask:0xf bound_ctrl:1
	s_waitcnt lgkmcnt(0)
	v_mov_b32_e32 v127, v126
	s_nop 1
	v_permlane16_swap_b32_e32 v126, v127
	s_nop 1
	v_add_f32_e32 v126, v126, v127
	s_waitcnt lgkmcnt(0)
	v_mov_b32_e32 v127, v126
	s_nop 1
	v_permlane32_swap_b32_e32 v126, v127
	s_nop 1
	v_add_f32_e32 v126, v126, v127
	v_fmamk_f32 v126, v126, 0x3a000000, v206
	v_cmp_gt_f32_e32 vcc, s3, v126
	v_mul_f32_e32 v127, 0x4b800000, v126
	s_nop 0
	v_cndmask_b32_e32 v126, v126, v127, vcc
	v_rsq_f32_e32 v126, v126
	s_nop 0
	v_mul_f32_e32 v127, 0x45800000, v126
	v_cndmask_b32_e32 v126, v126, v127, vcc
	v_pk_mul_f32 v[102:103], v[102:103], v[126:127] op_sel_hi:[1,0]
	v_pk_mul_f32 v[104:105], v[104:105], v[126:127] op_sel_hi:[1,0]
	v_pk_mul_f32 v[114:115], v[114:115], v[126:127] op_sel_hi:[1,0]
	v_pk_mul_f32 v[64:65], v[64:65], v[126:127] op_sel_hi:[1,0]
	v_pk_mul_f32 v[106:107], v[106:107], v[126:127] op_sel_hi:[1,0]
	v_pk_mul_f32 v[108:109], v[108:109], v[126:127] op_sel_hi:[1,0]
	v_pk_mul_f32 v[110:111], v[110:111], v[126:127] op_sel_hi:[1,0]
	v_pk_mul_f32 v[112:113], v[112:113], v[126:127] op_sel_hi:[1,0]
	v_pk_mul_f32 v[116:117], v[116:117], v[126:127] op_sel_hi:[1,0]
	s_waitcnt vmcnt(7)
	v_pk_fma_f32 v[28:29], v[4:5], v[102:103], v[28:29]
	v_pk_fma_f32 v[30:31], v[6:7], v[104:105], v[30:31]
	s_waitcnt vmcnt(4)
	v_pk_fma_f32 v[16:17], v[0:1], v[114:115], v[16:17]
	s_waitcnt vmcnt(0)
	v_pk_fma_f32 v[0:1], v[32:33], v[64:65], v[48:49]
	v_lshl_add_u64 v[32:33], s[4:5], 0, v[94:95]
	v_pk_fma_f32 v[24:25], v[12:13], v[106:107], v[24:25]
	v_pk_fma_f32 v[26:27], v[14:15], v[108:109], v[26:27]
	v_pk_fma_f32 v[20:21], v[8:9], v[110:111], v[20:21]
	v_pk_fma_f32 v[22:23], v[10:11], v[112:113], v[22:23]
	v_pk_fma_f32 v[18:19], v[2:3], v[116:117], v[18:19]
	global_store_dwordx4 v[32:33], v[28:31], off
	global_store_dwordx4 v[32:33], v[24:27], off offset:1024
	global_store_dwordx4 v[32:33], v[20:23], off offset:2048
	global_store_dwordx4 v[32:33], v[16:19], off offset:3072
	v_add_co_u32_e32 v32, vcc, s61, v32
	v_pk_mul_f32 v[118:119], v[118:119], v[126:127] op_sel_hi:[1,0]
	v_pk_mul_f32 v[120:121], v[120:121], v[126:127] op_sel_hi:[1,0]
	v_pk_mul_f32 v[122:123], v[122:123], v[126:127] op_sel_hi:[1,0]
	v_pk_mul_f32 v[124:125], v[124:125], v[126:127] op_sel_hi:[1,0]
	v_pk_mul_f32 v[130:131], v[130:131], v[126:127] op_sel_hi:[1,0]
	v_pk_mul_f32 v[132:133], v[132:133], v[126:127] op_sel_hi:[1,0]
	v_pk_mul_f32 v[66:67], v[66:67], v[126:127] op_sel_hi:[1,0]
	v_addc_co_u32_e32 v33, vcc, 0, v33, vcc
	v_pk_fma_f32 v[12:13], v[36:37], v[118:119], v[60:61]
	v_pk_fma_f32 v[14:15], v[38:39], v[120:121], v[62:63]
	v_pk_fma_f32 v[8:9], v[44:45], v[122:123], v[56:57]
	v_pk_fma_f32 v[10:11], v[46:47], v[124:125], v[58:59]
	v_pk_fma_f32 v[4:5], v[40:41], v[130:131], v[52:53]
	v_pk_fma_f32 v[6:7], v[42:43], v[132:133], v[54:55]
	v_pk_fma_f32 v[2:3], v[34:35], v[66:67], v[50:51]
	s_andn2_b64 vcc, exec, s[18:19]
	global_store_dwordx4 v[32:33], v[12:15], off
	global_store_dwordx4 v[32:33], v[8:11], off offset:1024
	global_store_dwordx4 v[32:33], v[4:7], off offset:2048
	global_store_dwordx4 v[32:33], v[0:3], off offset:3072
	s_cbranch_vccnz .LBB0_1151
	v_add_f32_e32 v32, 0, v28
	v_add_f32_e32 v32, v29, v32
	v_add_f32_e32 v32, v30, v32
	v_add_f32_e32 v32, v31, v32
	v_add_f32_e32 v32, v24, v32
	v_add_f32_e32 v32, v25, v32
	v_add_f32_e32 v32, v26, v32
	v_add_f32_e32 v32, v27, v32
	v_add_f32_e32 v32, v20, v32
	v_add_f32_e32 v32, v21, v32
	v_add_f32_e32 v32, v22, v32
	v_add_f32_e32 v32, v23, v32
	v_add_f32_e32 v32, v16, v32
	v_add_f32_e32 v32, v17, v32
	v_add_f32_e32 v32, v18, v32
	v_add_f32_e32 v32, v19, v32
	v_add_f32_e32 v32, v12, v32
	v_add_f32_e32 v32, v13, v32
	v_add_f32_e32 v32, v14, v32
	v_add_f32_e32 v32, v15, v32
	v_add_f32_e32 v32, v8, v32
	v_add_f32_e32 v32, v9, v32
	v_add_f32_e32 v32, v10, v32
	v_add_f32_e32 v32, v11, v32
	v_add_f32_e32 v32, v4, v32
	v_add_f32_e32 v32, v5, v32
	v_add_f32_e32 v32, v6, v32
	v_add_f32_e32 v32, v7, v32
	v_add_f32_e32 v32, v0, v32
	v_add_f32_e32 v32, v1, v32
	v_add_f32_e32 v32, v2, v32
	v_add_f32_e32 v32, v3, v32
	s_ashr_i32 s3, s2, 31
	s_lshr_b32 s3, s3, 21
	s_add_i32 s3, s2, s3
	s_ashr_i32 s3, s3, 11
	s_waitcnt lgkmcnt(0)
	s_nop 1
	v_add_f32_dpp v32, v32, v32 quad_perm:[1,0,3,2] row_mask:0xf bank_mask:0xf bound_ctrl:1
	s_cmpk_lt_i32 s2, 0x4000
	s_cselect_b32 s3, s3, 8
	s_ashr_i32 s7, s3, 31
	s_add_u32 s3, s3, s16
	s_waitcnt lgkmcnt(0)
	s_nop 1
	v_add_f32_dpp v32, v32, v32 quad_perm:[2,3,0,1] row_mask:0xf bank_mask:0xf bound_ctrl:1
	s_addc_u32 s7, s7, 0
	s_mul_hi_u32 s17, s3, 0xc000
	s_mul_i32 s7, s7, 0xc000
	s_mul_i32 s3, s3, 0xc000
	s_waitcnt lgkmcnt(0)
	s_nop 1
	v_add_f32_dpp v32, v32, v32 row_half_mirror row_mask:0xf bank_mask:0xf bound_ctrl:1
	s_add_i32 s17, s17, s7
	s_add_u32 s18, s14, s3
	s_addc_u32 s19, s15, s17
	v_lshl_add_u64 v[114:115], v[68:69], 2, s[18:19]
	s_waitcnt lgkmcnt(0)
	s_nop 1
	v_add_f32_dpp v32, v32, v32 row_mirror row_mask:0xf bank_mask:0xf bound_ctrl:1
	s_mov_b64 s[18:19], 0x2000
	s_movk_i32 s3, 0x3000
	v_lshl_add_u64 v[44:45], v[114:115], 0, s[18:19]
	s_waitcnt lgkmcnt(0)
; #define CBAR() asm volatile("" ::: "memory")
; DI void row_normalize(float (&v)[32]) {
;     float s = 0.f;
; #pragma unroll
;     for (int i = 0; i < 32; ++i) s += v[i];
;     const float mean = wave_sum(s) * (1.0f / D);
;     float q = 0.f;
; #pragma unroll
;     for (int i = 0; i < 32; ++i) { v[i] -= mean; q += v[i] * v[i]; }
;     const float rstd = rsqrtf(wave_sum(q) * (1.0f / D) + LN_EPS);
; DI void phase_peer_ln2(int l, int nrows, bool last, int wv) {
;     ...
;             const float* mdn = T.mod + ((size_t)(l + 1) * 9 + modrow(r)) * MODW;
;             row_normalize(v);
;             CBAR();
;             { float t[32]; load16_f32(mdn + 1 * D, lane, t);
; #pragma unroll
;               for (int i = 0; i < 32; ++i) v[i] *= (1.0f + t[i]); }
;             CBAR();
;             { float t[32]; load16_f32(mdn + 0 * D, lane, t);
	v_mov_b32_e32 v33, v32
	v_mov_b32_e32 v40, v32
	s_nop 1
	v_permlane16_swap_b32_e32 v40, v33
	s_nop 1
	v_add_f32_e32 v40, v40, v33
	v_add_co_u32_e32 v60, vcc, s3, v114
	global_load_dwordx4 v[32:35], v[44:45], off offset:1024
	global_load_dwordx4 v[36:39], v[44:45], off offset:2048
	v_addc_co_u32_e32 v61, vcc, 0, v115, vcc
	s_waitcnt lgkmcnt(0)
	v_mov_b32_e32 v41, v40
	s_nop 1
	v_permlane32_swap_b32_e32 v40, v41
	s_nop 1
	v_add_f32_e32 v40, v40, v41
	v_mul_f32_e32 v126, 0x3a000000, v40
	global_load_dwordx4 v[40:43], v[60:61], off offset:-4096
	s_nop 0
	global_load_dwordx4 v[44:47], v[44:45], off offset:3072
	s_nop 0
	global_load_dwordx4 v[48:51], v[60:61], off
	global_load_dwordx4 v[52:55], v[60:61], off offset:1024
	global_load_dwordx4 v[56:59], v[60:61], off offset:2048
	s_nop 0
	global_load_dwordx4 v[60:63], v[60:61], off offset:3072
	v_pk_add_f32 v[28:29], v[28:29], v[126:127] op_sel_hi:[1,0] neg_lo:[0,1] neg_hi:[0,1]
	global_load_dwordx4 v[64:67], v[114:115], off
	global_load_dwordx4 v[102:105], v[114:115], off offset:1024
	global_load_dwordx4 v[106:109], v[114:115], off offset:2048
	global_load_dwordx4 v[110:113], v[114:115], off offset:3072
	v_pk_mul_f32 v[134:135], v[28:29], v[28:29]
	v_pk_add_f32 v[30:31], v[30:31], v[126:127] op_sel_hi:[1,0] neg_lo:[0,1] neg_hi:[0,1]
	v_add_f32_e32 v128, v134, v135
	v_pk_mul_f32 v[136:137], v[30:31], v[30:31]
	v_pk_add_f32 v[24:25], v[24:25], v[126:127] op_sel_hi:[1,0] neg_lo:[0,1] neg_hi:[0,1]
	v_add_f32_e32 v128, v136, v128
	v_pk_mul_f32 v[138:139], v[24:25], v[24:25]
	v_add_f32_e32 v128, v137, v128
	v_pk_add_f32 v[26:27], v[26:27], v[126:127] op_sel_hi:[1,0] neg_lo:[0,1] neg_hi:[0,1]
	v_add_f32_e32 v128, v138, v128
	v_pk_mul_f32 v[140:141], v[26:27], v[26:27]
	v_add_f32_e32 v128, v139, v128
	v_pk_add_f32 v[20:21], v[20:21], v[126:127] op_sel_hi:[1,0] neg_lo:[0,1] neg_hi:[0,1]
	v_add_f32_e32 v128, v140, v128
	v_pk_mul_f32 v[142:143], v[20:21], v[20:21]
	v_add_f32_e32 v128, v141, v128
	v_pk_add_f32 v[22:23], v[22:23], v[126:127] op_sel_hi:[1,0] neg_lo:[0,1] neg_hi:[0,1]
	v_add_f32_e32 v128, v142, v128
	v_pk_mul_f32 v[144:145], v[22:23], v[22:23]
	v_add_f32_e32 v128, v143, v128
	v_pk_add_f32 v[16:17], v[16:17], v[126:127] op_sel_hi:[1,0] neg_lo:[0,1] neg_hi:[0,1]
	v_add_f32_e32 v128, v144, v128
	v_pk_mul_f32 v[146:147], v[16:17], v[16:17]
	v_add_f32_e32 v128, v145, v128
	v_pk_add_f32 v[18:19], v[18:19], v[126:127] op_sel_hi:[1,0] neg_lo:[0,1] neg_hi:[0,1]
	v_add_f32_e32 v128, v146, v128
	v_pk_mul_f32 v[148:149], v[18:19], v[18:19]
	v_add_f32_e32 v128, v147, v128
	v_pk_add_f32 v[12:13], v[12:13], v[126:127] op_sel_hi:[1,0] neg_lo:[0,1] neg_hi:[0,1]
	v_add_f32_e32 v128, v148, v128
	v_pk_mul_f32 v[150:151], v[12:13], v[12:13]
	v_add_f32_e32 v128, v149, v128
	v_pk_add_f32 v[14:15], v[14:15], v[126:127] op_sel_hi:[1,0] neg_lo:[0,1] neg_hi:[0,1]
	v_add_f32_e32 v128, v150, v128
	v_pk_mul_f32 v[152:153], v[14:15], v[14:15]
	v_add_f32_e32 v128, v151, v128
	v_pk_add_f32 v[8:9], v[8:9], v[126:127] op_sel_hi:[1,0] neg_lo:[0,1] neg_hi:[0,1]
	v_add_f32_e32 v128, v152, v128
	v_pk_mul_f32 v[154:155], v[8:9], v[8:9]
	v_add_f32_e32 v128, v153, v128
	v_pk_add_f32 v[10:11], v[10:11], v[126:127] op_sel_hi:[1,0] neg_lo:[0,1] neg_hi:[0,1]
	v_add_f32_e32 v128, v154, v128
	v_pk_mul_f32 v[156:157], v[10:11], v[10:11]
	v_add_f32_e32 v128, v155, v128
	v_pk_add_f32 v[4:5], v[4:5], v[126:127] op_sel_hi:[1,0] neg_lo:[0,1] neg_hi:[0,1]
	v_add_f32_e32 v128, v156, v128
	v_pk_mul_f32 v[158:159], v[4:5], v[4:5]
	v_add_f32_e32 v128, v157, v128
	v_pk_add_f32 v[6:7], v[6:7], v[126:127] op_sel_hi:[1,0] neg_lo:[0,1] neg_hi:[0,1]
	v_add_f32_e32 v128, v158, v128
	v_pk_mul_f32 v[160:161], v[6:7], v[6:7]
	v_add_f32_e32 v128, v159, v128
	v_pk_add_f32 v[0:1], v[0:1], v[126:127] op_sel_hi:[1,0] neg_lo:[0,1] neg_hi:[0,1]
	v_add_f32_e32 v128, v160, v128
	v_pk_mul_f32 v[162:163], v[0:1], v[0:1]
	v_add_f32_e32 v128, v161, v128
	v_pk_add_f32 v[2:3], v[2:3], v[126:127] op_sel_hi:[1,0] neg_lo:[0,1] neg_hi:[0,1]
	v_add_f32_e32 v128, v162, v128
	v_pk_mul_f32 v[126:127], v[2:3], v[2:3]
	v_add_f32_e32 v128, v163, v128
	v_add_f32_e32 v126, v126, v128
	v_add_f32_e32 v126, v127, v126
	v_add_co_u32_e32 v130, vcc, s61, v114
	s_mov_b32 s3, 0x800000
	s_nop 0
	v_addc_co_u32_e32 v131, vcc, 0, v115, vcc
	global_load_dwordx4 v[114:117], v[130:131], off
	global_load_dwordx4 v[118:121], v[130:131], off offset:1024
	global_load_dwordx4 v[122:125], v[130:131], off offset:2048
	s_nop 0
	global_load_dwordx4 v[130:133], v[130:131], off offset:3072
	s_waitcnt lgkmcnt(0)
	s_nop 1
	v_add_f32_dpp v126, v126, v126 quad_perm:[1,0,3,2] row_mask:0xf bank_mask:0xf bound_ctrl:1
	s_waitcnt vmcnt(15)
	v_pk_add_f32 v[32:33], v[32:33], 1.0 op_sel_hi:[1,0]
	s_waitcnt vmcnt(13)
	v_pk_add_f32 v[40:41], v[40:41], 1.0 op_sel_hi:[1,0]
	v_pk_add_f32 v[36:37], v[36:37], 1.0 op_sel_hi:[1,0]
	v_pk_add_f32 v[42:43], v[42:43], 1.0 op_sel_hi:[1,0]
	s_waitcnt lgkmcnt(0)
	s_nop 1
	v_add_f32_dpp v126, v126, v126 quad_perm:[2,3,0,1] row_mask:0xf bank_mask:0xf bound_ctrl:1
	v_pk_add_f32 v[34:35], v[34:35], 1.0 op_sel_hi:[1,0]
	v_pk_add_f32 v[38:39], v[38:39], 1.0 op_sel_hi:[1,0]
	s_waitcnt vmcnt(12)
	v_pk_add_f32 v[44:45], v[44:45], 1.0 op_sel_hi:[1,0]
	v_pk_add_f32 v[46:47], v[46:47], 1.0 op_sel_hi:[1,0]
	s_waitcnt lgkmcnt(0)
	s_nop 1
	v_add_f32_dpp v126, v126, v126 row_half_mirror row_mask:0xf bank_mask:0xf bound_ctrl:1
	s_waitcnt vmcnt(11)
	v_pk_add_f32 v[48:49], v[48:49], 1.0 op_sel_hi:[1,0]
	v_pk_add_f32 v[50:51], v[50:51], 1.0 op_sel_hi:[1,0]
	s_waitcnt vmcnt(10)
	v_pk_add_f32 v[52:53], v[52:53], 1.0 op_sel_hi:[1,0]
	v_pk_add_f32 v[54:55], v[54:55], 1.0 op_sel_hi:[1,0]
	s_waitcnt lgkmcnt(0)
; DI unsigned pk2(float lo, float hi) { unsigned r; asm("v_cvt_pk_bf16_f32 %0, %1, %2" : "=v"(r) : "v"(lo), "v"(hi)); return r; }
; DI unsigned pk4_fp8(float a, float b, float c, float d) { int w = 0; w = __builtin_amdgcn_cvt_pk_fp8_f32(clamp448(a), clamp448(b), w, false); w = __builtin_amdgcn_cvt_pk_fp8_f32(clamp448(c), clamp448(d), w, true); return (unsigned)w; }
; #define CBAR() asm volatile("" ::: "memory")
; DI void row_normalize(float (&v)[32]) {
;     ...
;     const float rstd = rsqrtf(wave_sum(q) * (1.0f / D) + LN_EPS);
; #pragma unroll
;     for (int i = 0; i < 32; ++i) v[i] *= rstd;
; DI void phase_peer_ln2(int l, int nrows, bool last, int wv) {
;     ...
;             row_normalize(v);
;             CBAR();
;             { float t[32]; load16_f32(mdn + 1 * D, lane, t);
; #pragma unroll
;               for (int i = 0; i < 32; ++i) v[i] *= (1.0f + t[i]); }
;             CBAR();
;             { float t[32]; load16_f32(mdn + 0 * D, lane, t);
; #pragma unroll
;               for (int i = 0; i < 32; ++i) v[i] += t[i]; }
; #pragma unroll
;             for (int c = 0; c < 8; ++c) { u32x2 wv2; wv2.x = pk2(v[c * 4 + 0], v[c * 4 + 1]); wv2.y = pk2(v[c * 4 + 2], v[c * 4 + 3]);
;                 *(u32x2*)(T.H + (size_t)r * D + c * 256 + lane * 4) = wv2;
;                 *(unsigned*)(T.ws + WS_H8 + (size_t)r * D + c * 256 + lane * 4) = pk4_fp8(v[c * 4 + 0] * SA8_H, v[c * 4 + 1] * SA8_H, v[c * 4 + 2] * SA8_H, v[c * 4 + 3] * SA8_H); }
	s_nop 1
	v_add_f32_dpp v126, v126, v126 row_mirror row_mask:0xf bank_mask:0xf bound_ctrl:1
	s_waitcnt vmcnt(9)
	v_pk_add_f32 v[56:57], v[56:57], 1.0 op_sel_hi:[1,0]
	v_pk_add_f32 v[58:59], v[58:59], 1.0 op_sel_hi:[1,0]
	s_waitcnt vmcnt(8)
	v_pk_add_f32 v[60:61], v[60:61], 1.0 op_sel_hi:[1,0]
	v_pk_add_f32 v[62:63], v[62:63], 1.0 op_sel_hi:[1,0]
	s_waitcnt lgkmcnt(0)
	v_mov_b32_e32 v127, v126
	s_nop 1
	v_permlane16_swap_b32_e32 v126, v127
	s_nop 1
	v_add_f32_e32 v126, v126, v127
	s_waitcnt lgkmcnt(0)
	v_mov_b32_e32 v127, v126
	s_nop 1
	v_permlane32_swap_b32_e32 v126, v127
	s_nop 1
	v_add_f32_e32 v126, v126, v127
	v_fmamk_f32 v126, v126, 0x3a000000, v206
	v_mul_f32_e32 v127, 0x4b800000, v126
	v_cmp_gt_f32_e32 vcc, s3, v126
	s_mov_b32 s3, 0x15c00000
	s_nop 0
	v_cndmask_b32_e32 v126, v126, v127, vcc
	v_rsq_f32_e32 v126, v126
	s_nop 0
	v_mul_f32_e32 v127, 0x45800000, v126
	v_cndmask_b32_e32 v126, v126, v127, vcc
	v_pk_mul_f32 v[24:25], v[24:25], v[126:127] op_sel_hi:[1,0]
	v_pk_mul_f32 v[28:29], v[28:29], v[126:127] op_sel_hi:[1,0]
	s_waitcnt vmcnt(6)
	v_pk_fma_f32 v[24:25], v[32:33], v[24:25], v[102:103]
	v_lshl_add_u64 v[32:33], s[0:1], 0, v[92:93]
	v_pk_mul_f32 v[20:21], v[20:21], v[126:127] op_sel_hi:[1,0]
	v_pk_fma_f32 v[28:29], v[40:41], v[28:29], v[64:65]
	v_add_co_u32_e32 v32, vcc, s3, v32
	v_pk_mul_f32 v[30:31], v[30:31], v[126:127] op_sel_hi:[1,0]
	s_waitcnt vmcnt(5)
	v_pk_fma_f32 v[20:21], v[36:37], v[20:21], v[106:107]
	v_cvt_pk_bf16_f32 v36, v28, v29
	v_addc_co_u32_e32 v33, vcc, 0, v33, vcc
	v_mul_f32_e32 v28, 0x41800000, v28
	v_mul_f32_e32 v29, 0x41800000, v29
	v_pk_fma_f32 v[30:31], v[42:43], v[30:31], v[66:67]
	v_med3_f32 v28, v28, s33, v238
	v_cvt_pk_bf16_f32 v37, v30, v31
	global_store_dwordx2 v[32:33], v[36:37], off
	v_med3_f32 v29, v29, s33, v238
	v_mov_b32_e32 v36, v129
	v_cvt_pk_fp8_f32 v36, v28, v29
	v_pk_mul_f32 v[26:27], v[26:27], v[126:127] op_sel_hi:[1,0]
	v_mul_f32_e32 v30, 0x41800000, v30
	v_mul_f32_e32 v28, 0x41800000, v31
	v_pk_fma_f32 v[26:27], v[34:35], v[26:27], v[104:105]
	v_lshl_add_u64 v[34:35], s[0:1], 0, v[90:91]
	v_med3_f32 v29, v30, s33, v238
	v_med3_f32 v28, v28, s33, v238
	s_mov_b32 s3, 0x43e00000
	v_cvt_pk_fp8_f32 v36, v29, v28 op_sel:[0,0,1]
	v_add_co_u32_e32 v28, vcc, s3, v34
	v_mul_f32_e32 v30, 0x41800000, v24
	v_mul_f32_e32 v31, 0x41800000, v25
	v_addc_co_u32_e32 v29, vcc, 0, v35, vcc
	v_med3_f32 v30, v30, s33, v238
	v_med3_f32 v31, v31, s33, v238
	v_mov_b32_e32 v35, v129
	v_cvt_pk_fp8_f32 v35, v30, v31
	v_mul_f32_e32 v34, 0x41800000, v26
	v_mul_f32_e32 v30, 0x41800000, v27
	v_med3_f32 v31, v34, s33, v238
	v_med3_f32 v30, v30, s33, v238
	v_cvt_pk_fp8_f32 v35, v31, v30 op_sel:[0,0,1]
	v_cvt_pk_bf16_f32 v24, v24, v25
	v_cvt_pk_bf16_f32 v25, v26, v27
	global_store_dword v[28:29], v36, off
	global_store_dwordx2 v[32:33], v[24:25], off offset:512
	global_store_dword v[28:29], v35, off offset:256
	v_mul_f32_e32 v24, 0x41800000, v20
	v_mul_f32_e32 v25, 0x41800000, v21
	v_med3_f32 v24, v24, s33, v238
	v_med3_f32 v25, v25, s33, v238
	v_mov_b32_e32 v27, v129
	v_pk_mul_f32 v[22:23], v[22:23], v[126:127] op_sel_hi:[1,0]
	v_cvt_pk_fp8_f32 v27, v24, v25
	v_pk_fma_f32 v[22:23], v[38:39], v[22:23], v[108:109]
	v_pk_mul_f32 v[16:17], v[16:17], v[126:127] op_sel_hi:[1,0]
	v_mul_f32_e32 v26, 0x41800000, v22
	v_mul_f32_e32 v24, 0x41800000, v23
	v_med3_f32 v25, v26, s33, v238
	v_med3_f32 v24, v24, s33, v238
	v_cvt_pk_fp8_f32 v27, v25, v24 op_sel:[0,0,1]
	s_waitcnt vmcnt(8)
; DI unsigned pk4_fp8(float a, float b, float c, float d) { int w = 0; w = __builtin_amdgcn_cvt_pk_fp8_f32(clamp448(a), clamp448(b), w, false); w = __builtin_amdgcn_cvt_pk_fp8_f32(clamp448(c), clamp448(d), w, true); return (unsigned)w; }
; DI unsigned pk2(float lo, float hi) { unsigned r; asm("v_cvt_pk_bf16_f32 %0, %1, %2" : "=v"(r) : "v"(lo), "v"(hi)); return r; }
; DI float clamp448(float x) { return fminf(fmaxf(x, -448.0f), 448.0f); }
; DI void phase_peer_ln2(int l, int nrows, bool last, int wv) {
;     ...
;             { float t[32]; load16_f32(mdn + 0 * D, lane, t);
; #pragma unroll
;               for (int i = 0; i < 32; ++i) v[i] += t[i]; }
; #pragma unroll
;             for (int c = 0; c < 8; ++c) { u32x2 wv2; wv2.x = pk2(v[c * 4 + 0], v[c * 4 + 1]); wv2.y = pk2(v[c * 4 + 2], v[c * 4 + 3]);
;                 *(u32x2*)(T.H + (size_t)r * D + c * 256 + lane * 4) = wv2;
;                 *(unsigned*)(T.ws + WS_H8 + (size_t)r * D + c * 256 + lane * 4) = pk4_fp8(v[c * 4 + 0] * SA8_H, v[c * 4 + 1] * SA8_H, v[c * 4 + 2] * SA8_H, v[c * 4 + 3] * SA8_H); }
	v_pk_fma_f32 v[16:17], v[44:45], v[16:17], v[110:111]
	v_cvt_pk_bf16_f32 v20, v20, v21
	v_cvt_pk_bf16_f32 v21, v22, v23
	global_store_dwordx2 v[32:33], v[20:21], off offset:1024
	global_store_dword v[28:29], v27, off offset:512
	v_mul_f32_e32 v20, 0x41800000, v16
	v_mul_f32_e32 v21, 0x41800000, v17
	v_med3_f32 v20, v20, s33, v238
	v_med3_f32 v21, v21, s33, v238
	v_mov_b32_e32 v23, v129
	v_pk_mul_f32 v[18:19], v[18:19], v[126:127] op_sel_hi:[1,0]
	v_cvt_pk_fp8_f32 v23, v20, v21
	v_pk_fma_f32 v[18:19], v[46:47], v[18:19], v[112:113]
	v_pk_mul_f32 v[12:13], v[12:13], v[126:127] op_sel_hi:[1,0]
	v_mul_f32_e32 v22, 0x41800000, v18
	v_mul_f32_e32 v20, 0x41800000, v19
	v_med3_f32 v21, v22, s33, v238
	v_med3_f32 v20, v20, s33, v238
	v_cvt_pk_fp8_f32 v23, v21, v20 op_sel:[0,0,1]
	s_waitcnt vmcnt(9)
	v_pk_fma_f32 v[12:13], v[48:49], v[12:13], v[114:115]
	v_cvt_pk_bf16_f32 v16, v16, v17
	v_cvt_pk_bf16_f32 v17, v18, v19
	global_store_dwordx2 v[32:33], v[16:17], off offset:1536
	global_store_dword v[28:29], v23, off offset:768
	v_mul_f32_e32 v16, 0x41800000, v12
	v_mul_f32_e32 v17, 0x41800000, v13
	v_med3_f32 v16, v16, s33, v238
	v_med3_f32 v17, v17, s33, v238
	v_mov_b32_e32 v19, v129
	v_pk_mul_f32 v[14:15], v[14:15], v[126:127] op_sel_hi:[1,0]
	v_cvt_pk_fp8_f32 v19, v16, v17
	v_pk_fma_f32 v[14:15], v[50:51], v[14:15], v[116:117]
	v_pk_mul_f32 v[8:9], v[8:9], v[126:127] op_sel_hi:[1,0]
	v_mul_f32_e32 v18, 0x41800000, v14
	v_mul_f32_e32 v16, 0x41800000, v15
	v_med3_f32 v17, v18, s33, v238
	v_med3_f32 v16, v16, s33, v238
	v_cvt_pk_fp8_f32 v19, v17, v16 op_sel:[0,0,1]
	s_waitcnt vmcnt(10)
	v_pk_fma_f32 v[8:9], v[52:53], v[8:9], v[118:119]
	v_cvt_pk_bf16_f32 v12, v12, v13
	v_cvt_pk_bf16_f32 v13, v14, v15
	global_store_dwordx2 v[32:33], v[12:13], off offset:2048
	global_store_dword v[28:29], v19, off offset:1024
	v_mul_f32_e32 v12, 0x41800000, v8
	v_mul_f32_e32 v13, 0x41800000, v9
	v_med3_f32 v12, v12, s33, v238
	v_med3_f32 v13, v13, s33, v238
	v_mov_b32_e32 v15, v129
	v_pk_mul_f32 v[10:11], v[10:11], v[126:127] op_sel_hi:[1,0]
	v_cvt_pk_fp8_f32 v15, v12, v13
	v_pk_fma_f32 v[10:11], v[54:55], v[10:11], v[120:121]
	v_pk_mul_f32 v[4:5], v[4:5], v[126:127] op_sel_hi:[1,0]
	v_mul_f32_e32 v14, 0x41800000, v10
	v_mul_f32_e32 v12, 0x41800000, v11
	v_med3_f32 v13, v14, s33, v238
	v_med3_f32 v12, v12, s33, v238
	v_cvt_pk_fp8_f32 v15, v13, v12 op_sel:[0,0,1]
	s_waitcnt vmcnt(11)
	v_pk_fma_f32 v[4:5], v[56:57], v[4:5], v[122:123]
	v_cvt_pk_bf16_f32 v8, v8, v9
	v_cvt_pk_bf16_f32 v9, v10, v11
	global_store_dwordx2 v[32:33], v[8:9], off offset:2560
	global_store_dword v[28:29], v15, off offset:1280
	v_mul_f32_e32 v8, 0x41800000, v4
	v_mul_f32_e32 v9, 0x41800000, v5
	v_med3_f32 v8, v8, s33, v238
	v_med3_f32 v9, v9, s33, v238
	v_mov_b32_e32 v11, v129
	v_pk_mul_f32 v[6:7], v[6:7], v[126:127] op_sel_hi:[1,0]
	v_cvt_pk_fp8_f32 v11, v8, v9
	v_pk_fma_f32 v[6:7], v[58:59], v[6:7], v[124:125]
	v_pk_mul_f32 v[0:1], v[0:1], v[126:127] op_sel_hi:[1,0]
	v_mul_f32_e32 v10, 0x41800000, v6
	v_mul_f32_e32 v8, 0x41800000, v7
	v_med3_f32 v9, v10, s33, v238
	v_med3_f32 v8, v8, s33, v238
	v_cvt_pk_fp8_f32 v11, v9, v8 op_sel:[0,0,1]
	s_waitcnt vmcnt(12)
	v_pk_fma_f32 v[0:1], v[60:61], v[0:1], v[130:131]
	v_cvt_pk_bf16_f32 v4, v4, v5
	v_cvt_pk_bf16_f32 v5, v6, v7
	global_store_dwordx2 v[32:33], v[4:5], off offset:3072
	global_store_dword v[28:29], v11, off offset:1536
	v_mul_f32_e32 v4, 0x41800000, v0
	v_mul_f32_e32 v5, 0x41800000, v1
	v_med3_f32 v4, v4, s33, v238
	v_med3_f32 v5, v5, s33, v238
	v_mov_b32_e32 v7, v129
	v_pk_mul_f32 v[2:3], v[2:3], v[126:127] op_sel_hi:[1,0]
	v_cvt_pk_fp8_f32 v7, v4, v5
	v_pk_fma_f32 v[2:3], v[62:63], v[2:3], v[132:133]
	v_cvt_pk_bf16_f32 v0, v0, v1
	s_nop 0
	v_mul_f32_e32 v6, 0x41800000, v2
	v_mul_f32_e32 v4, 0x41800000, v3
	v_med3_f32 v5, v6, s33, v238
	v_med3_f32 v4, v4, s33, v238
	v_cvt_pk_fp8_f32 v7, v5, v4 op_sel:[0,0,1]
	v_cvt_pk_bf16_f32 v1, v2, v3
	global_store_dwordx2 v[32:33], v[0:1], off offset:3584
	global_store_dword v[28:29], v7, off offset:1792
	s_branch .LBB0_1151
